# conv mixer tap loop: f16 partial sums added to the f32 accumulators with v_fma_mix_f32 (acc = f32(h)*1.0 + acc, same single rounding) instead of two converts plus a packed add
# speedup vs baseline: 1.0022x; 1.0022x over previous
; #define LAS __attribute__((address_space(3)))
; __global__ void __launch_bounds__(NWAVES * 64, 2) fwd_kernel(Args args) {
;     ...
;                 f16x8 win[15];
; #pragma unroll
;                 for (int i = 0; i < 7; ++i) win[8 + i] = *(const LAS f16x8*)(ub + i * CONV_CH);
; #pragma unroll 1
;                 for (int jj = 0; jj < 32; jj += 8) {
; #pragma unroll
;                     for (int i = 0; i < 7; ++i) win[i] = win[8 + i];
; #pragma unroll
;                     for (int i = 0; i < 8; ++i) win[7 + i] = *(const LAS f16x8*)(ub + (jj + 7 + i) * CONV_CH);
;                     f16x8 part[8];
; #pragma unroll
;                     for (int dj = 0; dj < 8; ++dj) {
;                         const f16x8 wj = *(const LAS f16x8*)(wb + (jj + dj) * CONV_CH);
; #pragma unroll
;                         for (int i = 0; i < 8; ++i) part[i] = (dj == 0) ? wj * win[i] : __builtin_elementwise_fma(wj, win[dj + i], part[i]);
;                     }
.LBB0_648:
	v_add_u32_e32 v78, s7, v208
	ds_read_b128 v[74:77], v208
	ds_read_b128 v[50:53], v208 offset:1024
	ds_read_b128 v[54:57], v208 offset:2048
	ds_read_b128 v[58:61], v208 offset:3072
	ds_read_b128 v[62:65], v208 offset:4096
	ds_read_b128 v[66:69], v208 offset:5120
	ds_read_b128 v[70:73], v208 offset:6144
	ds_read_b128 v[46:49], v208 offset:7168
	v_add_u32_e32 v79, 0xfffe8400, v78
	v_add_u32_e32 v80, 0xfffe8800, v78
	v_add_u32_e32 v81, 0xfffe8c00, v78
	v_add_u32_e32 v82, 0xfffe9000, v78
	v_add_u32_e32 v83, 0xfffe9400, v78
	v_add_u32_e32 v84, 0xfffe9800, v78
	v_add_u32_e32 v85, 0xfffe9c00, v78
	v_add_u32_e32 v78, 0xfffea000, v78
	s_waitcnt lgkmcnt(7)
	v_pk_mul_f16 v42, v74, v42
	v_pk_mul_f16 v43, v75, v43
	v_pk_mul_f16 v44, v76, v44
	v_pk_mul_f16 v45, v77, v45
	v_pk_mul_f16 v209, v74, v38
	v_pk_mul_f16 v222, v75, v39
	v_pk_mul_f16 v223, v76, v40
	v_pk_mul_f16 v224, v77, v41
	v_pk_mul_f16 v225, v74, v30
	v_pk_mul_f16 v226, v75, v31
	v_pk_mul_f16 v227, v76, v32
	v_pk_mul_f16 v228, v77, v33
	v_pk_mul_f16 v229, v74, v18
	v_pk_mul_f16 v230, v75, v19
	v_pk_mul_f16 v232, v77, v21
	v_pk_mul_f16 v233, v74, v22
	v_pk_mul_f16 v236, v77, v25
	v_pk_mul_f16 v237, v74, v26
	v_pk_mul_f16 v240, v77, v29
	ds_read_b128 v[210:213], v79
	ds_read_b128 v[214:217], v80
	ds_read_b128 v[218:221], v81
	ds_read_b128 v[94:97], v82
	ds_read_b128 v[90:93], v83
	ds_read_b128 v[86:89], v84
	ds_read_b128 v[82:85], v85
	ds_read_b128 v[78:81], v78
	v_pk_mul_f16 v231, v76, v20
	v_pk_mul_f16 v234, v75, v23
	v_pk_mul_f16 v235, v76, v24
	v_pk_mul_f16 v238, v75, v27
	v_pk_mul_f16 v239, v76, v28
	v_pk_mul_f16 v241, v74, v34
	v_pk_mul_f16 v242, v75, v35
	v_pk_mul_f16 v243, v76, v36
	v_pk_mul_f16 v244, v77, v37
	s_waitcnt lgkmcnt(14)
	v_pk_fma_f16 v41, v53, v41, v45
	v_pk_fma_f16 v40, v52, v40, v44
	v_pk_fma_f16 v39, v51, v39, v43
	v_pk_fma_f16 v38, v50, v38, v42
	v_pk_fma_f16 v42, v53, v33, v224
	v_pk_fma_f16 v43, v52, v32, v223
	v_pk_fma_f16 v44, v51, v31, v222
	v_pk_fma_f16 v45, v50, v30, v209
	v_pk_fma_f16 v209, v53, v21, v228
	v_pk_fma_f16 v222, v52, v20, v227
	v_pk_fma_f16 v223, v51, v19, v226
	v_pk_fma_f16 v224, v50, v18, v225
	v_pk_fma_f16 v225, v53, v25, v232
	v_pk_fma_f16 v227, v51, v23, v230
	v_pk_fma_f16 v228, v50, v22, v229
	v_pk_fma_f16 v229, v53, v29, v236
	v_pk_fma_f16 v232, v50, v26, v233
	v_pk_fma_f16 v233, v53, v37, v240
	v_pk_fma_f16 v236, v50, v34, v237
	s_waitcnt lgkmcnt(7)
	v_pk_mul_f16 v74, v74, v210
	v_pk_mul_f16 v75, v75, v211
	v_pk_mul_f16 v76, v76, v212
	v_pk_mul_f16 v77, v77, v213
	v_pk_fma_f16 v226, v52, v24, v231
	v_pk_fma_f16 v230, v52, v28, v235
	v_pk_fma_f16 v231, v51, v27, v234
	v_pk_fma_f16 v234, v52, v36, v239
	v_pk_fma_f16 v235, v51, v35, v238
	v_pk_fma_f16 v237, v53, v213, v244
	v_pk_fma_f16 v238, v52, v212, v243
	v_pk_fma_f16 v239, v51, v211, v242
	v_pk_fma_f16 v240, v50, v210, v241
	v_pk_fma_f16 v241, v54, v30, v38
	v_pk_fma_f16 v242, v55, v31, v39
	v_pk_fma_f16 v243, v56, v32, v40
	v_pk_fma_f16 v244, v57, v33, v41
	v_pk_fma_f16 v245, v54, v18, v45
	v_pk_fma_f16 v246, v55, v19, v44
	v_pk_fma_f16 v247, v56, v20, v43
	v_pk_fma_f16 v248, v57, v21, v42
	v_pk_fma_f16 v224, v54, v22, v224
	v_pk_fma_f16 v223, v55, v23, v223
	v_pk_fma_f16 v222, v56, v24, v222
	v_pk_fma_f16 v209, v57, v25, v209
	v_pk_fma_f16 v228, v54, v26, v228
	v_pk_fma_f16 v227, v55, v27, v227
	v_pk_fma_f16 v225, v57, v29, v225
	v_pk_fma_f16 v232, v54, v34, v232
	v_pk_fma_f16 v229, v57, v37, v229
	v_pk_fma_f16 v236, v54, v210, v236
	v_pk_fma_f16 v233, v57, v213, v233
	s_waitcnt lgkmcnt(6)
	v_pk_fma_f16 v53, v53, v217, v77
	v_pk_fma_f16 v52, v52, v216, v76
	v_pk_fma_f16 v51, v51, v215, v75
	v_pk_fma_f16 v50, v50, v214, v74
	v_pk_fma_f16 v226, v56, v28, v226
	v_pk_fma_f16 v231, v55, v35, v231
	v_pk_fma_f16 v230, v56, v36, v230
	v_pk_fma_f16 v235, v55, v211, v235
	v_pk_fma_f16 v234, v56, v212, v234
	v_pk_fma_f16 v74, v54, v214, v240
	v_pk_fma_f16 v75, v55, v215, v239
	v_pk_fma_f16 v76, v56, v216, v238
	v_pk_fma_f16 v77, v57, v217, v237
	v_pk_fma_f16 v237, v61, v21, v244
	v_pk_fma_f16 v238, v60, v20, v243
	v_pk_fma_f16 v239, v59, v19, v242
	v_pk_fma_f16 v240, v58, v18, v241
	v_pk_fma_f16 v241, v61, v25, v248
	v_pk_fma_f16 v242, v60, v24, v247
	v_pk_fma_f16 v243, v59, v23, v246
	v_pk_fma_f16 v244, v58, v22, v245
	v_pk_fma_f16 v209, v61, v29, v209
	v_pk_fma_f16 v222, v60, v28, v222
	v_pk_fma_f16 v223, v59, v27, v223
	v_pk_fma_f16 v224, v58, v26, v224
	v_pk_fma_f16 v225, v61, v37, v225
	v_pk_fma_f16 v227, v59, v35, v227
	v_pk_fma_f16 v228, v58, v34, v228
	v_pk_fma_f16 v229, v61, v213, v229
	v_pk_fma_f16 v232, v58, v210, v232
	v_pk_fma_f16 v233, v61, v217, v233
	v_pk_fma_f16 v236, v58, v214, v236
	s_waitcnt lgkmcnt(5)
	v_pk_fma_f16 v50, v54, v218, v50
	v_pk_fma_f16 v51, v55, v219, v51
	v_pk_fma_f16 v52, v56, v220, v52
	v_pk_fma_f16 v53, v57, v221, v53
	v_pk_fma_f16 v226, v60, v36, v226
	v_pk_fma_f16 v230, v60, v212, v230
	v_pk_fma_f16 v231, v59, v211, v231
	v_pk_fma_f16 v234, v60, v216, v234
	v_pk_fma_f16 v235, v59, v215, v235
	v_pk_fma_f16 v54, v61, v221, v77
	v_pk_fma_f16 v55, v60, v220, v76
	v_pk_fma_f16 v56, v59, v219, v75
	v_pk_fma_f16 v57, v58, v218, v74
	v_pk_fma_f16 v74, v62, v22, v240
	v_pk_fma_f16 v75, v63, v23, v239
	v_pk_fma_f16 v76, v64, v24, v238
	v_pk_fma_f16 v77, v65, v25, v237
	v_pk_fma_f16 v237, v62, v26, v244
	v_pk_fma_f16 v238, v63, v27, v243
	v_pk_fma_f16 v239, v64, v28, v242
	v_pk_fma_f16 v240, v65, v29, v241
	v_pk_fma_f16 v224, v62, v34, v224
	v_pk_fma_f16 v223, v63, v35, v223
	v_pk_fma_f16 v222, v64, v36, v222
	v_pk_fma_f16 v209, v65, v37, v209
	v_pk_fma_f16 v228, v62, v210, v228
	v_pk_fma_f16 v227, v63, v211, v227
	v_pk_fma_f16 v225, v65, v213, v225
	v_pk_fma_f16 v232, v62, v214, v232
	v_pk_fma_f16 v229, v65, v217, v229
	v_pk_fma_f16 v236, v62, v218, v236
	v_pk_fma_f16 v233, v65, v221, v233
	s_waitcnt lgkmcnt(4)
; #define LAS __attribute__((address_space(3)))
; __global__ void __launch_bounds__(NWAVES * 64, 2) fwd_kernel(Args args) {
;     ...
;                 for (int jj = 0; jj < 32; jj += 8) {
; #pragma unroll
;                     for (int i = 0; i < 7; ++i) win[i] = win[8 + i];
; #pragma unroll
;                     for (int i = 0; i < 8; ++i) win[7 + i] = *(const LAS f16x8*)(ub + (jj + 7 + i) * CONV_CH);
;                     f16x8 part[8];
; #pragma unroll
;                     for (int dj = 0; dj < 8; ++dj) {
;                         const f16x8 wj = *(const LAS f16x8*)(wb + (jj + dj) * CONV_CH);
; #pragma unroll
;                         for (int i = 0; i < 8; ++i) part[i] = (dj == 0) ? wj * win[i] : __builtin_elementwise_fma(wj, win[dj + i], part[i]);
;                     }
; #pragma unroll
;                     for (int i = 0; i < 8; ++i)
; #pragma unroll
;                         for (int e = 0; e < 8; ++e) acc[i][e] += (float)part[i][e];
	v_pk_fma_f16 v53, v61, v97, v53
	v_pk_fma_f16 v52, v60, v96, v52
	v_pk_fma_f16 v51, v59, v95, v51
	v_pk_fma_f16 v50, v58, v94, v50
	v_pk_fma_f16 v226, v64, v212, v226
	v_pk_fma_f16 v231, v63, v215, v231
	v_pk_fma_f16 v230, v64, v216, v230
	v_pk_fma_f16 v235, v63, v219, v235
	v_pk_fma_f16 v234, v64, v220, v234
	v_pk_fma_f16 v57, v62, v94, v57
	v_pk_fma_f16 v56, v63, v95, v56
	v_pk_fma_f16 v55, v64, v96, v55
	v_pk_fma_f16 v54, v65, v97, v54
	v_pk_fma_f16 v58, v69, v29, v77
	v_pk_fma_f16 v59, v68, v28, v76
	v_pk_fma_f16 v60, v67, v27, v75
	v_pk_fma_f16 v61, v66, v26, v74
	v_pk_fma_f16 v74, v69, v37, v240
	v_pk_fma_f16 v75, v68, v36, v239
	v_pk_fma_f16 v76, v67, v35, v238
	v_pk_fma_f16 v77, v66, v34, v237
	v_pk_fma_f16 v209, v69, v213, v209
	v_pk_fma_f16 v222, v68, v212, v222
	v_pk_fma_f16 v223, v67, v211, v223
	v_pk_fma_f16 v224, v66, v210, v224
	v_pk_fma_f16 v225, v69, v217, v225
	v_pk_fma_f16 v227, v67, v215, v227
	v_pk_fma_f16 v228, v66, v214, v228
	v_pk_fma_f16 v229, v69, v221, v229
	v_pk_fma_f16 v232, v66, v218, v232
	v_pk_fma_f16 v233, v69, v97, v233
	v_pk_fma_f16 v236, v66, v94, v236
	s_waitcnt lgkmcnt(3)
	v_pk_fma_f16 v50, v62, v90, v50
	v_pk_fma_f16 v51, v63, v91, v51
	v_pk_fma_f16 v52, v64, v92, v52
	v_pk_fma_f16 v53, v65, v93, v53
	v_mov_b64_e32 v[30:31], v[94:95]
	v_mov_b64_e32 v[42:43], v[214:215]
	v_pk_fma_f16 v226, v68, v216, v226
	v_pk_fma_f16 v230, v68, v220, v230
	v_pk_fma_f16 v231, v67, v219, v231
	v_pk_fma_f16 v234, v68, v96, v234
	v_pk_fma_f16 v235, v67, v95, v235
	v_pk_fma_f16 v54, v69, v93, v54
	v_pk_fma_f16 v55, v68, v92, v55
	v_pk_fma_f16 v56, v67, v91, v56
	v_pk_fma_f16 v57, v66, v90, v57
	v_pk_fma_f16 v59, v72, v36, v59
	v_pk_fma_f16 v62, v70, v210, v77
	v_pk_fma_f16 v63, v71, v211, v76
	v_pk_fma_f16 v64, v72, v212, v75
	v_pk_fma_f16 v65, v73, v213, v74
	v_pk_fma_f16 v74, v70, v214, v224
	v_pk_fma_f16 v75, v71, v215, v223
	v_pk_fma_f16 v76, v72, v216, v222
	v_pk_fma_f16 v77, v73, v217, v209
	v_pk_fma_f16 v209, v70, v218, v228
	v_pk_fma_f16 v222, v71, v219, v227
	v_pk_fma_f16 v224, v73, v221, v225
	v_pk_fma_f16 v225, v70, v94, v232
	v_pk_fma_f16 v228, v73, v97, v229
	v_pk_fma_f16 v229, v70, v90, v236
	v_pk_fma_f16 v232, v73, v93, v233
	s_waitcnt lgkmcnt(2)
	v_pk_fma_f16 v53, v69, v89, v53
	v_pk_fma_f16 v52, v68, v88, v52
	v_pk_fma_f16 v51, v67, v87, v51
	v_pk_fma_f16 v50, v66, v86, v50
	v_mov_b64_e32 v[32:33], v[96:97]
	v_mov_b64_e32 v[38:39], v[218:219]
	v_mov_b64_e32 v[44:45], v[216:217]
	v_mov_b64_e32 v[18:19], v[90:91]
	v_pk_fma_f16 v61, v70, v34, v61
	v_pk_fma_f16 v60, v71, v35, v60
	v_pk_fma_f16 v58, v73, v37, v58
	v_pk_fma_f16 v223, v72, v220, v226
	v_pk_fma_f16 v226, v71, v95, v231
	v_pk_fma_f16 v227, v72, v96, v230
	v_pk_fma_f16 v230, v71, v91, v235
	v_pk_fma_f16 v231, v72, v92, v234
	v_pk_fma_f16 v57, v70, v86, v57
	v_pk_fma_f16 v56, v71, v87, v56
	v_pk_fma_f16 v55, v72, v88, v55
	v_pk_fma_f16 v54, v73, v89, v54
	v_pk_fma_f16 v59, v48, v212, v59
	v_pk_fma_f16 v65, v49, v217, v65
	v_pk_fma_f16 v64, v48, v216, v64
	v_pk_fma_f16 v63, v47, v215, v63
	v_pk_fma_f16 v62, v46, v214, v62
	v_pk_fma_f16 v77, v49, v221, v77
	v_pk_fma_f16 v76, v48, v220, v76
	v_pk_fma_f16 v69, v47, v219, v75
	v_pk_fma_f16 v95, v47, v95, v222
	v_pk_fma_f16 v75, v46, v94, v209
	v_pk_fma_f16 v209, v49, v89, v232
	v_pk_fma_f16 v212, v46, v86, v229
	s_waitcnt lgkmcnt(1)
	v_pk_fma_f16 v214, v70, v82, v50
	v_pk_fma_f16 v215, v71, v83, v51
	v_pk_fma_f16 v216, v72, v84, v52
	v_pk_fma_f16 v217, v73, v85, v53
	v_mov_b64_e32 v[40:41], v[220:221]
	v_mov_b64_e32 v[20:21], v[92:93]
	v_mov_b64_e32 v[22:23], v[86:87]
	v_mov_b64_e32 v[26:27], v[82:83]
	s_waitcnt lgkmcnt(0)
	v_mov_b64_e32 v[34:35], v[78:79]
	v_pk_fma_f16 v58, v49, v213, v58
	v_pk_fma_f16 v60, v47, v211, v60
	v_pk_fma_f16 v61, v46, v210, v61
	v_pk_fma_f16 v67, v46, v218, v74
	v_pk_fma_f16 v97, v49, v97, v224
	v_pk_fma_f16 v96, v48, v96, v223
	v_pk_fma_f16 v93, v49, v93, v228
	v_pk_fma_f16 v92, v48, v92, v227
	v_pk_fma_f16 v91, v47, v91, v226
	v_pk_fma_f16 v90, v46, v90, v225
	v_pk_fma_f16 v211, v48, v88, v231
	v_pk_fma_f16 v210, v47, v87, v230
	v_pk_fma_f16 v218, v49, v85, v54
	v_pk_fma_f16 v219, v48, v84, v55
	v_pk_fma_f16 v220, v47, v83, v56
	v_pk_fma_f16 v221, v46, v82, v57
	v_fma_mix_f32 v162, v76, 1.0, v162 op_sel_hi:[1,0,0]
	v_fma_mix_f32 v163, v76, 1.0, v163 op_sel:[1,0,0] op_sel_hi:[1,0,0]
	v_fma_mix_f32 v164, v77, 1.0, v164 op_sel_hi:[1,0,0]
	v_fma_mix_f32 v165, v77, 1.0, v165 op_sel:[1,0,0] op_sel_hi:[1,0,0]
	v_fma_mix_f32 v154, v95, 1.0, v154 op_sel_hi:[1,0,0]
	v_fma_mix_f32 v155, v95, 1.0, v155 op_sel:[1,0,0] op_sel_hi:[1,0,0]
	v_fma_mix_f32 v140, v212, 1.0, v140 op_sel_hi:[1,0,0]
	v_fma_mix_f32 v141, v212, 1.0, v141 op_sel:[1,0,0] op_sel_hi:[1,0,0]
	v_fma_mix_f32 v134, v209, 1.0, v134 op_sel_hi:[1,0,0]
	v_fma_mix_f32 v135, v209, 1.0, v135 op_sel:[1,0,0] op_sel_hi:[1,0,0]
	v_pk_fma_f16 v209, v49, v81, v217
	v_pk_fma_f16 v222, v48, v80, v216
	v_pk_fma_f16 v217, v47, v79, v215
	v_pk_fma_f16 v215, v46, v78, v214
	v_mov_b64_e32 v[24:25], v[88:89]
	v_mov_b64_e32 v[28:29], v[84:85]
	v_mov_b64_e32 v[36:37], v[80:81]
	v_fma_mix_f32 v180, v61, 1.0, v180 op_sel_hi:[1,0,0]
	v_fma_mix_f32 v181, v61, 1.0, v181 op_sel:[1,0,0] op_sel_hi:[1,0,0]
	v_fma_mix_f32 v178, v60, 1.0, v178 op_sel_hi:[1,0,0]
	v_fma_mix_f32 v179, v60, 1.0, v179 op_sel:[1,0,0] op_sel_hi:[1,0,0]
	v_fma_mix_f32 v176, v59, 1.0, v176 op_sel_hi:[1,0,0]
	v_fma_mix_f32 v177, v59, 1.0, v177 op_sel:[1,0,0] op_sel_hi:[1,0,0]
	v_fma_mix_f32 v174, v58, 1.0, v174 op_sel_hi:[1,0,0]
	v_fma_mix_f32 v175, v58, 1.0, v175 op_sel:[1,0,0] op_sel_hi:[1,0,0]
	v_fma_mix_f32 v172, v62, 1.0, v172 op_sel_hi:[1,0,0]
; __global__ void __launch_bounds__(NWAVES * 64, 2) fwd_kernel(Args args) {
;     ...
; #pragma unroll
;                     for (int i = 0; i < 8; ++i)
; #pragma unroll
;                         for (int e = 0; e < 8; ++e) acc[i][e] += (float)part[i][e];
;                 }
;                 float gam[8], bet[8], cb[8];
; #pragma unroll
;                 for (int e = 0; e < 8; ++e) { gam[e] = conv_ln_g[c0 + e]; bet[e] = conv_ln_b[c0 + e]; cb[e] = conv_b[c0 + e]; }
;                 float sm[8], sq[8];
; #pragma unroll
;                 for (int i = 0; i < 8; ++i) { float s_ = 0.f;
; #pragma unroll
;                     for (int e = 0; e < 8; ++e) { acc[i][e] += cb[e]; s_ += acc[i][e]; }
;                     sm[i] = s_; }
;                 wave_sum_n<8>(sm);
; #pragma unroll
;                 for (int i = 0; i < 8; ++i) { const float mu = sm[i] * (1.0f / CONV_CH); sm[i] = mu; float q_ = 0.f;
; #pragma unroll
;                     for (int e = 0; e < 8; ++e) { acc[i][e] -= mu; q_ += acc[i][e] * acc[i][e]; }
;                     sq[i] = q_; }
;                 wave_sum_n<8>(sq);
	v_fma_mix_f32 v173, v62, 1.0, v173 op_sel:[1,0,0] op_sel_hi:[1,0,0]
	v_fma_mix_f32 v170, v63, 1.0, v170 op_sel_hi:[1,0,0]
	v_fma_mix_f32 v171, v63, 1.0, v171 op_sel:[1,0,0] op_sel_hi:[1,0,0]
	v_fma_mix_f32 v168, v64, 1.0, v168 op_sel_hi:[1,0,0]
	v_fma_mix_f32 v169, v64, 1.0, v169 op_sel:[1,0,0] op_sel_hi:[1,0,0]
	v_fma_mix_f32 v166, v65, 1.0, v166 op_sel_hi:[1,0,0]
	v_fma_mix_f32 v167, v65, 1.0, v167 op_sel:[1,0,0] op_sel_hi:[1,0,0]
	v_fma_mix_f32 v158, v67, 1.0, v158 op_sel_hi:[1,0,0]
	v_fma_mix_f32 v159, v67, 1.0, v159 op_sel:[1,0,0] op_sel_hi:[1,0,0]
	v_fma_mix_f32 v160, v69, 1.0, v160 op_sel_hi:[1,0,0]
	v_fma_mix_f32 v161, v69, 1.0, v161 op_sel:[1,0,0] op_sel_hi:[1,0,0]
	v_fma_mix_f32 v156, v75, 1.0, v156 op_sel_hi:[1,0,0]
	v_fma_mix_f32 v157, v75, 1.0, v157 op_sel:[1,0,0] op_sel_hi:[1,0,0]
	v_fma_mix_f32 v152, v96, 1.0, v152 op_sel_hi:[1,0,0]
	v_fma_mix_f32 v153, v96, 1.0, v153 op_sel:[1,0,0] op_sel_hi:[1,0,0]
	v_fma_mix_f32 v150, v97, 1.0, v150 op_sel_hi:[1,0,0]
	v_fma_mix_f32 v151, v97, 1.0, v151 op_sel:[1,0,0] op_sel_hi:[1,0,0]
	v_fma_mix_f32 v148, v90, 1.0, v148 op_sel_hi:[1,0,0]
	v_fma_mix_f32 v149, v90, 1.0, v149 op_sel:[1,0,0] op_sel_hi:[1,0,0]
	v_fma_mix_f32 v146, v91, 1.0, v146 op_sel_hi:[1,0,0]
	v_fma_mix_f32 v147, v91, 1.0, v147 op_sel:[1,0,0] op_sel_hi:[1,0,0]
	v_fma_mix_f32 v144, v92, 1.0, v144 op_sel_hi:[1,0,0]
	v_fma_mix_f32 v145, v92, 1.0, v145 op_sel:[1,0,0] op_sel_hi:[1,0,0]
	v_fma_mix_f32 v142, v93, 1.0, v142 op_sel_hi:[1,0,0]
	v_fma_mix_f32 v143, v93, 1.0, v143 op_sel:[1,0,0] op_sel_hi:[1,0,0]
	v_fma_mix_f32 v138, v210, 1.0, v138 op_sel_hi:[1,0,0]
	v_fma_mix_f32 v139, v210, 1.0, v139 op_sel:[1,0,0] op_sel_hi:[1,0,0]
	v_fma_mix_f32 v136, v211, 1.0, v136 op_sel_hi:[1,0,0]
	v_fma_mix_f32 v137, v211, 1.0, v137 op_sel:[1,0,0] op_sel_hi:[1,0,0]
	v_fma_mix_f32 v132, v221, 1.0, v132 op_sel_hi:[1,0,0]
	v_fma_mix_f32 v133, v221, 1.0, v133 op_sel:[1,0,0] op_sel_hi:[1,0,0]
	v_fma_mix_f32 v130, v220, 1.0, v130 op_sel_hi:[1,0,0]
	v_fma_mix_f32 v131, v220, 1.0, v131 op_sel:[1,0,0] op_sel_hi:[1,0,0]
	v_fma_mix_f32 v128, v219, 1.0, v128 op_sel_hi:[1,0,0]
	v_fma_mix_f32 v129, v219, 1.0, v129 op_sel:[1,0,0] op_sel_hi:[1,0,0]
	v_fma_mix_f32 v126, v218, 1.0, v126 op_sel_hi:[1,0,0]
	v_fma_mix_f32 v127, v218, 1.0, v127 op_sel:[1,0,0] op_sel_hi:[1,0,0]
	v_fma_mix_f32 v124, v215, 1.0, v124 op_sel_hi:[1,0,0]
	v_fma_mix_f32 v125, v215, 1.0, v125 op_sel:[1,0,0] op_sel_hi:[1,0,0]
	v_fma_mix_f32 v122, v217, 1.0, v122 op_sel_hi:[1,0,0]
	v_fma_mix_f32 v123, v217, 1.0, v123 op_sel:[1,0,0] op_sel_hi:[1,0,0]
	v_fma_mix_f32 v120, v222, 1.0, v120 op_sel_hi:[1,0,0]
	v_fma_mix_f32 v121, v222, 1.0, v121 op_sel:[1,0,0] op_sel_hi:[1,0,0]
	v_fma_mix_f32 v118, v209, 1.0, v118 op_sel_hi:[1,0,0]
	v_fma_mix_f32 v119, v209, 1.0, v119 op_sel:[1,0,0] op_sel_hi:[1,0,0]
	s_add_i32 s0, s0, 8
	v_add_u32_e32 v208, 0x2000, v208
	s_cmp_lt_u32 s0, 24
	s_cbranch_scc1 .LBB0_648
	global_load_dwordx4 v[22:25], v[116:117], off offset:16
	global_load_dwordx4 v[18:21], v[116:117], off
	s_add_i32 s0, s14, s6
	s_ashr_i32 s1, s0, 31
	s_lshl_b64 s[8:9], s[0:1], 11
	s_add_i32 s11, s11, s69
	s_waitcnt vmcnt(1)
	v_pk_add_f32 v[44:45], v[22:23], v[176:177]
	s_waitcnt vmcnt(0)
	v_pk_add_f32 v[48:49], v[18:19], v[180:181]
	v_pk_add_f32 v[56:57], v[18:19], v[172:173]
	v_add_f32_e32 v26, 0, v48
	v_add_f32_e32 v27, 0, v56
	v_pk_add_f32 v[46:47], v[20:21], v[178:179]
	v_pk_add_f32 v[54:55], v[20:21], v[170:171]
	v_add_f32_e32 v26, v26, v49
	v_add_f32_e32 v27, v27, v57
	v_add_f32_e32 v26, v26, v46
	v_add_f32_e32 v27, v27, v54
	v_pk_add_f32 v[52:53], v[22:23], v[168:169]
	v_add_f32_e32 v26, v26, v47
	v_add_f32_e32 v27, v27, v55
	v_add_f32_e32 v26, v26, v44
	v_add_f32_e32 v27, v27, v52
	v_pk_add_f32 v[42:43], v[24:25], v[174:175]
	v_pk_add_f32 v[50:51], v[24:25], v[166:167]
	v_add_f32_e32 v26, v26, v45
	v_add_f32_e32 v27, v27, v53
	v_add_f32_e32 v26, v26, v42
	v_add_f32_e32 v27, v27, v50
	v_add_f32_e32 v26, v26, v43
	v_add_f32_e32 v27, v27, v51
	ds_bpermute_b32 v28, v184, v26
	ds_bpermute_b32 v29, v184, v27
	s_waitcnt lgkmcnt(1)
	v_add_f32_e32 v26, v26, v28
	s_waitcnt lgkmcnt(0)
	v_add_f32_e32 v27, v27, v29
	ds_bpermute_b32 v28, v185, v26
	ds_bpermute_b32 v29, v185, v27
	s_waitcnt lgkmcnt(1)
	v_add_f32_e32 v26, v26, v28
	s_waitcnt lgkmcnt(0)
	v_add_f32_e32 v27, v27, v29
	ds_bpermute_b32 v28, v186, v26
	ds_bpermute_b32 v29, v186, v27
	s_waitcnt lgkmcnt(1)
	v_add_f32_e32 v26, v26, v28
	s_waitcnt lgkmcnt(0)
	v_add_f32_e32 v27, v27, v29
	ds_bpermute_b32 v28, v187, v26
	ds_bpermute_b32 v29, v187, v27
	s_waitcnt lgkmcnt(1)
	v_add_f32_e32 v58, v26, v28
	s_waitcnt lgkmcnt(0)
	v_add_f32_e32 v59, v27, v29
	global_load_dwordx4 v[26:29], v[106:107], off offset:16
	global_load_dwordx4 v[34:37], v[106:107], off
	global_load_dwordx4 v[30:33], v[114:115], off offset:16
	global_load_dwordx4 v[38:41], v[114:115], off
	ds_bpermute_b32 v60, v188, v58
	ds_bpermute_b32 v61, v188, v59
	s_waitcnt lgkmcnt(1)
	v_add_f32_e32 v60, v58, v60
	s_waitcnt lgkmcnt(0)
	v_add_f32_e32 v61, v59, v61
	ds_bpermute_b32 v62, v189, v60
	ds_bpermute_b32 v63, v189, v61
	v_lshl_add_u64 v[58:59], v[104:105], 0, s[8:9]
	s_or_b32 s8, s0, 1
	s_ashr_i32 s9, s8, 31
	s_waitcnt lgkmcnt(1)
	v_add_f32_e32 v60, v60, v62
	s_waitcnt lgkmcnt(0)
; __device__ __forceinline__ unsigned pkh8(float lo, float hi) { return rnd8a(pkh(lo, hi)); }
; __device__ __forceinline__ float sigmoidf_(float x) { return __builtin_amdgcn_rcpf(1.0f + __builtin_amdgcn_exp2f(-x * LOG2E)); }
; __global__ void __launch_bounds__(NWAVES * 64, 2) fwd_kernel(Args args) {
;     ...
;                 wave_sum_n<8>(sm);
; #pragma unroll
;                 for (int i = 0; i < 8; ++i) { const float mu = sm[i] * (1.0f / CONV_CH); sm[i] = mu; float q_ = 0.f;
; #pragma unroll
;                     for (int e = 0; e < 8; ++e) { acc[i][e] -= mu; q_ += acc[i][e] * acc[i][e]; }
;                     sq[i] = q_; }
;                 wave_sum_n<8>(sq);
; #pragma unroll
;                 for (int i = 0; i < 8; ++i) {
;                     const float rstd = __builtin_amdgcn_rsqf(sq[i] * (1.0f / CONV_CH) + EPS);
;                     float y[8];
; #pragma unroll
;                     for (int e = 0; e < 8; ++e) { const float z = acc[i][e] * rstd * gam[e] + bet[e]; y[e] = z * sigmoidf_(z); }
;                     u32x4 w; w.x = pkh8(y[0], y[1]); w.y = pkh8(y[2], y[3]); w.z = pkh8(y[4], y[5]); w.w = pkh8(y[6], y[7]);
;                     *(u32x4*)(MIX + (size_t)(t0 + wave * 8 + i) * D + c0) = w;
;                 }
	v_add_f32_e32 v61, v61, v63
	v_mul_f32_e32 v60, 0x3b000000, v60
	v_mul_f32_e32 v62, 0x3b000000, v61
	v_pk_add_f32 v[48:49], v[48:49], v[60:61] op_sel_hi:[1,0] neg_lo:[0,1] neg_hi:[0,1]
	v_pk_add_f32 v[46:47], v[46:47], v[60:61] op_sel_hi:[1,0] neg_lo:[0,1] neg_hi:[0,1]
	v_pk_add_f32 v[44:45], v[44:45], v[60:61] op_sel_hi:[1,0] neg_lo:[0,1] neg_hi:[0,1]
	v_pk_add_f32 v[60:61], v[42:43], v[60:61] op_sel_hi:[1,0] neg_lo:[0,1] neg_hi:[0,1]
	v_pk_add_f32 v[42:43], v[50:51], v[62:63] op_sel_hi:[1,0] neg_lo:[0,1] neg_hi:[0,1]
	v_pk_mul_f32 v[50:51], v[48:49], v[48:49]
	v_pk_add_f32 v[56:57], v[56:57], v[62:63] op_sel_hi:[1,0] neg_lo:[0,1] neg_hi:[0,1]
	v_pk_add_f32 v[54:55], v[54:55], v[62:63] op_sel_hi:[1,0] neg_lo:[0,1] neg_hi:[0,1]
	v_pk_add_f32 v[52:53], v[52:53], v[62:63] op_sel_hi:[1,0] neg_lo:[0,1] neg_hi:[0,1]
	v_pk_mul_f32 v[62:63], v[46:47], v[46:47]
	v_add_f32_e32 v50, v50, v51
	v_pk_mul_f32 v[68:69], v[56:57], v[56:57]
	v_add_f32_e32 v50, v50, v62
	v_pk_mul_f32 v[64:65], v[44:45], v[44:45]
	v_pk_mul_f32 v[70:71], v[54:55], v[54:55]
	v_add_f32_e32 v51, v68, v69
	v_add_f32_e32 v50, v50, v63
	v_add_f32_e32 v51, v51, v70
	v_add_f32_e32 v50, v50, v64
	v_pk_mul_f32 v[66:67], v[60:61], v[60:61]
	v_pk_mul_f32 v[72:73], v[52:53], v[52:53]
	v_add_f32_e32 v51, v51, v71
	v_add_f32_e32 v50, v50, v65
	v_add_f32_e32 v51, v51, v72
	v_add_f32_e32 v50, v50, v66
	v_pk_mul_f32 v[74:75], v[42:43], v[42:43]
	v_add_f32_e32 v51, v51, v73
	v_add_f32_e32 v62, v50, v67
	ds_bpermute_b32 v63, v184, v62
	v_add_f32_e32 v50, v51, v74
	v_add_f32_e32 v64, v50, v75
	ds_bpermute_b32 v65, v184, v64
	v_pk_add_f32 v[50:51], v[24:25], v[164:165]
	s_waitcnt lgkmcnt(1)
	v_add_f32_e32 v66, v62, v63
	ds_bpermute_b32 v67, v185, v66
	v_pk_add_f32 v[62:63], v[22:23], v[162:163]
	s_waitcnt lgkmcnt(1)
	v_add_f32_e32 v68, v64, v65
	ds_bpermute_b32 v69, v185, v68
	v_pk_add_f32 v[64:65], v[20:21], v[160:161]
	s_waitcnt lgkmcnt(1)
	v_add_f32_e32 v70, v66, v67
	ds_bpermute_b32 v71, v186, v70
	v_pk_add_f32 v[66:67], v[18:19], v[158:159]
	s_waitcnt lgkmcnt(1)
	v_add_f32_e32 v68, v68, v69
	ds_bpermute_b32 v69, v186, v68
	v_add_f32_e32 v72, 0, v66
	s_waitcnt lgkmcnt(1)
	v_add_f32_e32 v70, v70, v71
	ds_bpermute_b32 v71, v187, v70
	v_add_f32_e32 v72, v72, v67
	s_waitcnt lgkmcnt(1)
	v_add_f32_e32 v68, v68, v69
	ds_bpermute_b32 v69, v187, v68
	v_add_f32_e32 v72, v72, v64
	s_waitcnt lgkmcnt(1)
	v_add_f32_e32 v70, v70, v71
	ds_bpermute_b32 v71, v188, v70
	v_add_f32_e32 v72, v72, v65
	s_waitcnt lgkmcnt(1)
	v_add_f32_e32 v68, v68, v69
	ds_bpermute_b32 v69, v188, v68
	v_add_f32_e32 v72, v72, v62
	s_waitcnt lgkmcnt(1)
	v_add_f32_e32 v70, v70, v71
	ds_bpermute_b32 v71, v189, v70
	v_add_f32_e32 v72, v72, v63
	s_waitcnt lgkmcnt(1)
	v_add_f32_e32 v69, v68, v69
	ds_bpermute_b32 v73, v189, v69
	v_add_f32_e32 v78, v72, v50
	s_waitcnt lgkmcnt(1)
	v_add_f32_e32 v68, v70, v71
	v_fmamk_f32 v68, v68, 0x3b000000, v207
	v_rsq_f32_e32 v68, v68
	s_waitcnt lgkmcnt(0)
	v_add_f32_e32 v69, v69, v73
	v_fmamk_f32 v69, v69, 0x3b000000, v207
	v_rsq_f32_e32 v70, v69
	v_pk_mul_f32 v[48:49], v[68:69], v[48:49] op_sel_hi:[0,1]
	v_pk_mul_f32 v[46:47], v[68:69], v[46:47] op_sel_hi:[0,1]
	v_pk_mul_f32 v[44:45], v[68:69], v[44:45] op_sel_hi:[0,1]
	v_pk_mul_f32 v[60:61], v[68:69], v[60:61] op_sel_hi:[0,1]
	s_waitcnt vmcnt(0)
	v_pk_fma_f32 v[48:49], v[48:49], v[34:35], v[38:39]
	v_pk_fma_f32 v[46:47], v[46:47], v[36:37], v[40:41]
	v_pk_fma_f32 v[44:45], v[44:45], v[26:27], v[30:31]
	v_pk_mul_f32 v[56:57], v[70:71], v[56:57] op_sel_hi:[0,1]
	v_pk_fma_f32 v[60:61], v[60:61], v[28:29], v[32:33]
	v_mul_f32_e32 v68, 0xbfb8aa3b, v48
	v_mul_f32_e32 v69, 0xbfb8aa3b, v49
	v_mul_f32_e32 v71, 0xbfb8aa3b, v46
	v_mul_f32_e32 v72, 0xbfb8aa3b, v47
	v_mul_f32_e32 v73, 0xbfb8aa3b, v44
	v_mul_f32_e32 v74, 0xbfb8aa3b, v45
	v_pk_fma_f32 v[56:57], v[56:57], v[34:35], v[38:39]
	v_mul_f32_e32 v75, 0xbfb8aa3b, v60
	v_mul_f32_e32 v76, 0xbfb8aa3b, v61
	v_exp_f32_e32 v68, v68
	v_exp_f32_e32 v69, v69
	v_exp_f32_e32 v71, v71
	v_exp_f32_e32 v72, v72
	v_exp_f32_e32 v73, v73
	v_exp_f32_e32 v74, v74
	v_mul_f32_e32 v77, 0xbfb8aa3b, v56
	v_exp_f32_e32 v75, v75
	v_exp_f32_e32 v76, v76
	v_exp_f32_e32 v77, v77
	v_add_f32_e32 v68, 1.0, v68
	v_add_f32_e32 v69, 1.0, v69
	v_add_f32_e32 v71, 1.0, v71
	v_add_f32_e32 v80, 1.0, v72
	v_add_f32_e32 v81, 1.0, v73
	v_add_f32_e32 v82, 1.0, v74
	v_add_f32_e32 v83, 1.0, v75
	v_add_f32_e32 v84, 1.0, v76
	v_rcp_f32_e32 v68, v68
	v_rcp_f32_e32 v69, v69
	v_rcp_f32_e32 v72, v71
	v_rcp_f32_e32 v73, v80
	v_rcp_f32_e32 v74, v81
	v_rcp_f32_e32 v75, v82
	v_add_f32_e32 v85, 1.0, v77
	v_rcp_f32_e32 v76, v83
	v_rcp_f32_e32 v77, v84
	v_pk_mul_f32 v[48:49], v[48:49], v[68:69]
	v_pk_mul_f32 v[46:47], v[46:47], v[72:73]
	v_pk_mul_f32 v[44:45], v[44:45], v[74:75]
	v_pk_mul_f32 v[60:61], v[60:61], v[76:77]
	v_cvt_pk_f16_f32 v48, v48, v49
	v_cvt_pk_f16_f32 v46, v46, v47
	v_cvt_pk_f16_f32 v44, v44, v45
	v_cvt_pk_f16_f32 v45, v60, v61
	v_add_u32_e32 v47, 0x40004, v48
	v_add_u32_e32 v46, 0x40004, v46
	v_add_u32_e32 v48, 0x40004, v44
	v_add_u32_e32 v49, 0x40004, v45
	v_and_b32_e32 v45, 0xfff8fff8, v46
	v_and_b32_e32 v46, 0xfff8fff8, v48
	v_add_f32_e32 v48, v78, v51
	v_and_b32_e32 v44, 0xfff8fff8, v47
	v_and_b32_e32 v47, 0xfff8fff8, v49
	ds_bpermute_b32 v49, v184, v48
	v_mul_f32_e32 v79, 0xbfb8aa3b, v57
	v_exp_f32_e32 v79, v79
	global_store_dwordx4 v[58:59], v[44:47], off
	v_pk_mul_f32 v[52:53], v[70:71], v[52:53] op_sel_hi:[0,1]
	s_waitcnt lgkmcnt(0)
	v_add_f32_e32 v48, v48, v49
	ds_bpermute_b32 v49, v185, v48
	v_pk_mul_f32 v[46:47], v[70:71], v[54:55] op_sel_hi:[0,1]
	v_pk_fma_f32 v[46:47], v[46:47], v[36:37], v[40:41]
	v_add_f32_e32 v45, 1.0, v79
	v_mul_f32_e32 v54, 0xbfb8aa3b, v46
	s_waitcnt lgkmcnt(0)
; __device__ __forceinline__ unsigned pkh8(float lo, float hi) { return rnd8a(pkh(lo, hi)); }
; __device__ __forceinline__ float sigmoidf_(float x) { return __builtin_amdgcn_rcpf(1.0f + __builtin_amdgcn_exp2f(-x * LOG2E)); }
; __global__ void __launch_bounds__(NWAVES * 64, 2) fwd_kernel(Args args) {
;     ...
;                 for (int i = 0; i < 8; ++i) { const float mu = sm[i] * (1.0f / CONV_CH); sm[i] = mu; float q_ = 0.f;
; #pragma unroll
;                     for (int e = 0; e < 8; ++e) { acc[i][e] -= mu; q_ += acc[i][e] * acc[i][e]; }
;                     sq[i] = q_; }
;                 wave_sum_n<8>(sq);
; #pragma unroll
;                 for (int i = 0; i < 8; ++i) {
;                     const float rstd = __builtin_amdgcn_rsqf(sq[i] * (1.0f / CONV_CH) + EPS);
;                     float y[8];
; #pragma unroll
;                     for (int e = 0; e < 8; ++e) { const float z = acc[i][e] * rstd * gam[e] + bet[e]; y[e] = z * sigmoidf_(z); }
;                     u32x4 w; w.x = pkh8(y[0], y[1]); w.y = pkh8(y[2], y[3]); w.z = pkh8(y[4], y[5]); w.w = pkh8(y[6], y[7]);
;                     *(u32x4*)(MIX + (size_t)(t0 + wave * 8 + i) * D + c0) = w;
;                 }
	v_add_f32_e32 v49, v48, v49
	ds_bpermute_b32 v55, v186, v49
	v_rcp_f32_e32 v44, v85
	v_rcp_f32_e32 v45, v45
	v_exp_f32_e32 v54, v54
	v_pk_fma_f32 v[52:53], v[52:53], v[26:27], v[30:31]
	s_waitcnt lgkmcnt(0)
	v_add_f32_e32 v55, v49, v55
	v_pk_mul_f32 v[44:45], v[56:57], v[44:45]
	v_add_f32_e32 v48, 1.0, v54
	v_mul_f32_e32 v54, 0xbfb8aa3b, v47
	ds_bpermute_b32 v56, v187, v55
	v_exp_f32_e32 v54, v54
	v_mul_f32_e32 v57, 0xbfb8aa3b, v53
	v_rcp_f32_e32 v48, v48
	v_exp_f32_e32 v57, v57
	v_add_f32_e32 v49, 1.0, v54
	s_waitcnt lgkmcnt(0)
	v_add_f32_e32 v54, v55, v56
	ds_bpermute_b32 v55, v188, v54
	v_mul_f32_e32 v56, 0xbfb8aa3b, v52
	v_rcp_f32_e32 v49, v49
	v_exp_f32_e32 v56, v56
	v_pk_mul_f32 v[42:43], v[70:71], v[42:43] op_sel_hi:[0,1]
	s_waitcnt lgkmcnt(0)
	v_add_f32_e32 v54, v54, v55
	ds_bpermute_b32 v55, v189, v54
	v_pk_mul_f32 v[46:47], v[46:47], v[48:49]
	v_add_f32_e32 v48, 1.0, v56
	v_add_f32_e32 v49, 1.0, v57
	v_pk_fma_f32 v[42:43], v[42:43], v[28:29], v[32:33]
	s_waitcnt lgkmcnt(0)
	v_add_f32_e32 v54, v54, v55
	v_mul_f32_e32 v54, 0x3b000000, v54
	v_pk_add_f32 v[56:57], v[66:67], v[54:55] op_sel_hi:[1,0] neg_lo:[0,1] neg_hi:[0,1]
	v_pk_add_f32 v[60:61], v[64:65], v[54:55] op_sel_hi:[1,0] neg_lo:[0,1] neg_hi:[0,1]
	v_pk_mul_f32 v[58:59], v[56:57], v[56:57]
	v_pk_mul_f32 v[64:65], v[60:61], v[60:61]
	v_add_f32_e32 v58, v58, v59
	v_pk_add_f32 v[62:63], v[62:63], v[54:55] op_sel_hi:[1,0] neg_lo:[0,1] neg_hi:[0,1]
	v_add_f32_e32 v58, v58, v64
	v_pk_mul_f32 v[66:67], v[62:63], v[62:63]
	v_add_f32_e32 v58, v58, v65
	v_pk_add_f32 v[50:51], v[50:51], v[54:55] op_sel_hi:[1,0] neg_lo:[0,1] neg_hi:[0,1]
	v_add_f32_e32 v58, v58, v66
	v_pk_mul_f32 v[54:55], v[50:51], v[50:51]
	v_add_f32_e32 v58, v58, v67
	v_add_f32_e32 v54, v58, v54
	v_add_f32_e32 v54, v54, v55
	ds_bpermute_b32 v55, v184, v54
	v_mul_f32_e32 v58, 0xbfb8aa3b, v42
	v_exp_f32_e32 v58, v58
	v_mul_f32_e32 v59, 0xbfb8aa3b, v43
	v_exp_f32_e32 v59, v59
	s_waitcnt lgkmcnt(0)
	v_add_f32_e32 v54, v54, v55
	ds_bpermute_b32 v55, v185, v54
	v_add_f32_e32 v58, 1.0, v58
	v_rcp_f32_e32 v48, v48
	v_rcp_f32_e32 v49, v49
	s_lshl_b64 s[8:9], s[8:9], 11
	s_waitcnt lgkmcnt(0)
	v_add_f32_e32 v64, v54, v55
	ds_bpermute_b32 v65, v186, v64
	v_rcp_f32_e32 v54, v58
	v_add_f32_e32 v55, 1.0, v59
	v_rcp_f32_e32 v55, v55
	v_pk_mul_f32 v[48:49], v[52:53], v[48:49]
	s_waitcnt lgkmcnt(0)
	v_add_f32_e32 v58, v64, v65
	ds_bpermute_b32 v59, v187, v58
	v_pk_mul_f32 v[52:53], v[42:43], v[54:55]
	v_cvt_pk_f16_f32 v42, v44, v45
	v_cvt_pk_f16_f32 v43, v46, v47
	v_cvt_pk_f16_f32 v46, v48, v49
	s_waitcnt lgkmcnt(0)
	v_add_f32_e32 v44, v58, v59
	ds_bpermute_b32 v45, v188, v44
	v_add_u32_e32 v42, 0x40004, v42
	v_add_u32_e32 v43, 0x40004, v43
	v_pk_add_f32 v[54:55], v[18:19], v[156:157]
	v_and_b32_e32 v42, 0xfff8fff8, v42
	s_waitcnt lgkmcnt(0)
	v_add_f32_e32 v45, v44, v45
	ds_bpermute_b32 v47, v189, v45
	v_add_u32_e32 v44, 0x40004, v46
	v_cvt_pk_f16_f32 v46, v52, v53
	v_add_u32_e32 v48, 0x40004, v46
	v_and_b32_e32 v43, 0xfff8fff8, v43
	s_waitcnt lgkmcnt(0)
	v_add_f32_e32 v45, v45, v47
	v_fmamk_f32 v45, v45, 0x3b000000, v207
	v_rsq_f32_e32 v46, v45
	v_and_b32_e32 v44, 0xfff8fff8, v44
	v_and_b32_e32 v45, 0xfff8fff8, v48
	v_lshl_add_u64 v[52:53], v[104:105], 0, s[8:9]
	v_pk_mul_f32 v[48:49], v[46:47], v[56:57] op_sel_hi:[0,1]
	v_add_f32_e32 v56, 0, v54
	global_store_dwordx4 v[52:53], v[42:45], off
	v_pk_add_f32 v[52:53], v[20:21], v[154:155]
	v_add_f32_e32 v56, v56, v55
	v_add_f32_e32 v56, v56, v52
	v_pk_fma_f32 v[48:49], v[48:49], v[34:35], v[38:39]
	v_pk_add_f32 v[44:45], v[22:23], v[152:153]
	v_add_f32_e32 v56, v56, v53
	v_mul_f32_e32 v42, 0xbfb8aa3b, v49
	v_add_f32_e32 v56, v56, v44
	v_exp_f32_e32 v57, v42
	v_pk_add_f32 v[42:43], v[24:25], v[150:151]
	v_add_f32_e32 v56, v56, v45
	v_mul_f32_e32 v47, 0xbfb8aa3b, v48
	v_add_f32_e32 v56, v56, v42
	v_exp_f32_e32 v47, v47
	v_add_f32_e32 v64, v56, v43
	ds_bpermute_b32 v65, v184, v64
	s_or_b32 s8, s0, 2
	v_add_f32_e32 v47, 1.0, v47
	v_rcp_f32_e32 v56, v47
	v_add_f32_e32 v47, 1.0, v57
	v_rcp_f32_e32 v57, v47
	v_pk_mul_f32 v[58:59], v[46:47], v[60:61] op_sel_hi:[0,1]
	s_waitcnt lgkmcnt(0)
	v_add_f32_e32 v47, v64, v65
	ds_bpermute_b32 v60, v185, v47
	v_pk_mul_f32 v[48:49], v[48:49], v[56:57]
	v_pk_fma_f32 v[58:59], v[58:59], v[36:37], v[40:41]
	s_ashr_i32 s9, s8, 31
	v_mul_f32_e32 v61, 0xbfb8aa3b, v58
	s_waitcnt lgkmcnt(0)
	v_add_f32_e32 v47, v47, v60
	ds_bpermute_b32 v57, v186, v47
	v_mul_f32_e32 v60, 0xbfb8aa3b, v59
	v_exp_f32_e32 v61, v61
	v_exp_f32_e32 v60, v60
	s_lshl_b64 s[8:9], s[8:9], 11
	s_waitcnt lgkmcnt(0)
	v_add_f32_e32 v47, v47, v57
	ds_bpermute_b32 v64, v187, v47
	v_add_f32_e32 v56, 1.0, v61
	v_add_f32_e32 v57, 1.0, v60
	v_pk_mul_f32 v[60:61], v[46:47], v[62:63] op_sel_hi:[0,1]
	v_pk_fma_f32 v[60:61], v[60:61], v[26:27], v[30:31]
	s_waitcnt lgkmcnt(0)
	v_add_f32_e32 v47, v47, v64
	ds_bpermute_b32 v62, v188, v47
	v_mul_f32_e32 v63, 0xbfb8aa3b, v60
	v_exp_f32_e32 v63, v63
	v_mul_f32_e32 v64, 0xbfb8aa3b, v61
	v_rcp_f32_e32 v56, v56
	s_waitcnt lgkmcnt(0)
	v_add_f32_e32 v47, v47, v62
	ds_bpermute_b32 v62, v189, v47
	v_rcp_f32_e32 v57, v57
	v_exp_f32_e32 v64, v64
	s_waitcnt lgkmcnt(0)
; __device__ __forceinline__ unsigned pkh8(float lo, float hi) { return rnd8a(pkh(lo, hi)); }
; __device__ __forceinline__ float sigmoidf_(float x) { return __builtin_amdgcn_rcpf(1.0f + __builtin_amdgcn_exp2f(-x * LOG2E)); }
; __global__ void __launch_bounds__(NWAVES * 64, 2) fwd_kernel(Args args) {
;     ...
;                 for (int i = 0; i < 8; ++i) { const float mu = sm[i] * (1.0f / CONV_CH); sm[i] = mu; float q_ = 0.f;
; #pragma unroll
;                     for (int e = 0; e < 8; ++e) { acc[i][e] -= mu; q_ += acc[i][e] * acc[i][e]; }
;                     sq[i] = q_; }
;                 wave_sum_n<8>(sq);
; #pragma unroll
;                 for (int i = 0; i < 8; ++i) {
;                     const float rstd = __builtin_amdgcn_rsqf(sq[i] * (1.0f / CONV_CH) + EPS);
;                     float y[8];
; #pragma unroll
;                     for (int e = 0; e < 8; ++e) { const float z = acc[i][e] * rstd * gam[e] + bet[e]; y[e] = z * sigmoidf_(z); }
;                     u32x4 w; w.x = pkh8(y[0], y[1]); w.y = pkh8(y[2], y[3]); w.z = pkh8(y[4], y[5]); w.w = pkh8(y[6], y[7]);
;                     *(u32x4*)(MIX + (size_t)(t0 + wave * 8 + i) * D + c0) = w;
;                 }
	v_add_f32_e32 v47, v47, v62
	v_mul_f32_e32 v62, 0x3b000000, v47
	v_pk_add_f32 v[54:55], v[54:55], v[62:63] op_sel_hi:[1,0] neg_lo:[0,1] neg_hi:[0,1]
	v_pk_mul_f32 v[56:57], v[58:59], v[56:57]
	v_add_f32_e32 v59, 1.0, v64
	v_pk_mul_f32 v[64:65], v[54:55], v[54:55]
	v_pk_add_f32 v[52:53], v[52:53], v[62:63] op_sel_hi:[1,0] neg_lo:[0,1] neg_hi:[0,1]
	v_add_f32_e32 v47, v64, v65
	v_pk_mul_f32 v[66:67], v[52:53], v[52:53]
	v_pk_add_f32 v[68:69], v[44:45], v[62:63] op_sel_hi:[1,0] neg_lo:[0,1] neg_hi:[0,1]
	v_add_f32_e32 v47, v47, v66
	v_pk_mul_f32 v[44:45], v[68:69], v[68:69]
	v_add_f32_e32 v47, v47, v67
	v_add_f32_e32 v58, 1.0, v63
	v_pk_add_f32 v[62:63], v[42:43], v[62:63] op_sel_hi:[1,0] neg_lo:[0,1] neg_hi:[0,1]
	v_add_f32_e32 v44, v47, v44
	v_pk_mul_f32 v[42:43], v[62:63], v[62:63]
	v_add_f32_e32 v44, v44, v45
	v_add_f32_e32 v42, v44, v42
	v_add_f32_e32 v44, v42, v43
	ds_bpermute_b32 v45, v184, v44
	v_pk_mul_f32 v[42:43], v[46:47], v[50:51] op_sel_hi:[0,1]
	v_pk_fma_f32 v[42:43], v[42:43], v[28:29], v[32:33]
	v_rcp_f32_e32 v58, v58
	v_mul_f32_e32 v46, 0xbfb8aa3b, v42
	s_waitcnt lgkmcnt(0)
	v_add_f32_e32 v44, v44, v45
	ds_bpermute_b32 v45, v185, v44
	v_exp_f32_e32 v46, v46
	v_mul_f32_e32 v47, 0xbfb8aa3b, v43
	v_rcp_f32_e32 v59, v59
	v_exp_f32_e32 v47, v47
	s_waitcnt lgkmcnt(0)
	v_add_f32_e32 v50, v44, v45
	ds_bpermute_b32 v51, v186, v50
	v_add_f32_e32 v46, 1.0, v46
	v_rcp_f32_e32 v44, v46
	v_add_f32_e32 v45, 1.0, v47
	v_pk_mul_f32 v[46:47], v[60:61], v[58:59]
	s_waitcnt lgkmcnt(0)
	v_add_f32_e32 v58, v50, v51
	ds_bpermute_b32 v59, v187, v58
	v_rcp_f32_e32 v45, v45
	v_cvt_pk_f16_f32 v46, v46, v47
	v_pk_mul_f32 v[50:51], v[42:43], v[44:45]
	s_waitcnt lgkmcnt(0)
	v_add_f32_e32 v44, v58, v59
	ds_bpermute_b32 v45, v188, v44
	v_cvt_pk_f16_f32 v42, v48, v49
	v_cvt_pk_f16_f32 v43, v56, v57
	v_add_u32_e32 v42, 0x40004, v42
	v_add_u32_e32 v43, 0x40004, v43
	s_waitcnt lgkmcnt(0)
	v_add_f32_e32 v45, v44, v45
	ds_bpermute_b32 v47, v189, v45
	v_add_u32_e32 v44, 0x40004, v46
	v_cvt_pk_f16_f32 v46, v50, v51
	v_add_u32_e32 v48, 0x40004, v46
	v_and_b32_e32 v42, 0xfff8fff8, v42
	s_waitcnt lgkmcnt(0)
	v_add_f32_e32 v45, v45, v47
	v_fmamk_f32 v45, v45, 0x3b000000, v207
	v_rsq_f32_e32 v46, v45
	v_and_b32_e32 v45, 0xfff8fff8, v48
	v_and_b32_e32 v43, 0xfff8fff8, v43
	v_and_b32_e32 v44, 0xfff8fff8, v44
	v_pk_mul_f32 v[48:49], v[46:47], v[54:55] op_sel_hi:[0,1]
	v_pk_add_f32 v[54:55], v[18:19], v[148:149]
	v_lshl_add_u64 v[50:51], v[104:105], 0, s[8:9]
	v_add_f32_e32 v56, 0, v54
	global_store_dwordx4 v[50:51], v[42:45], off
	v_pk_add_f32 v[50:51], v[20:21], v[146:147]
	v_add_f32_e32 v56, v56, v55
	v_add_f32_e32 v56, v56, v50
	v_pk_fma_f32 v[48:49], v[48:49], v[34:35], v[38:39]
	v_pk_add_f32 v[44:45], v[22:23], v[144:145]
	v_add_f32_e32 v56, v56, v51
	v_mul_f32_e32 v42, 0xbfb8aa3b, v49
	v_add_f32_e32 v56, v56, v44
	v_exp_f32_e32 v57, v42
	v_pk_add_f32 v[42:43], v[24:25], v[142:143]
	v_add_f32_e32 v56, v56, v45
	v_mul_f32_e32 v47, 0xbfb8aa3b, v48
	v_add_f32_e32 v56, v56, v42
	v_exp_f32_e32 v47, v47
	v_add_f32_e32 v58, v56, v43
	ds_bpermute_b32 v59, v184, v58
	s_or_b32 s8, s0, 3
	v_add_f32_e32 v47, 1.0, v47
	v_rcp_f32_e32 v56, v47
	v_add_f32_e32 v47, 1.0, v57
	v_rcp_f32_e32 v57, v47
	v_pk_mul_f32 v[52:53], v[46:47], v[52:53] op_sel_hi:[0,1]
	s_waitcnt lgkmcnt(0)
	v_add_f32_e32 v47, v58, v59
	ds_bpermute_b32 v58, v185, v47
	v_pk_mul_f32 v[48:49], v[48:49], v[56:57]
	v_pk_fma_f32 v[52:53], v[52:53], v[36:37], v[40:41]
	s_ashr_i32 s9, s8, 31
	v_mul_f32_e32 v59, 0xbfb8aa3b, v52
	s_waitcnt lgkmcnt(0)
	v_add_f32_e32 v47, v47, v58
	ds_bpermute_b32 v57, v186, v47
	v_mul_f32_e32 v58, 0xbfb8aa3b, v53
	v_exp_f32_e32 v59, v59
	v_exp_f32_e32 v58, v58
	s_lshl_b64 s[8:9], s[8:9], 11
	s_waitcnt lgkmcnt(0)
	v_add_f32_e32 v47, v47, v57
	ds_bpermute_b32 v60, v187, v47
	v_add_f32_e32 v56, 1.0, v59
	v_add_f32_e32 v57, 1.0, v58
	v_pk_mul_f32 v[58:59], v[46:47], v[68:69] op_sel_hi:[0,1]
	v_pk_fma_f32 v[58:59], v[58:59], v[26:27], v[30:31]
	s_waitcnt lgkmcnt(0)
	v_add_f32_e32 v47, v47, v60
	ds_bpermute_b32 v60, v188, v47
	v_mul_f32_e32 v61, 0xbfb8aa3b, v58
	v_exp_f32_e32 v61, v61
	v_mul_f32_e32 v64, 0xbfb8aa3b, v59
	v_rcp_f32_e32 v56, v56
	s_waitcnt lgkmcnt(0)
	v_add_f32_e32 v47, v47, v60
	ds_bpermute_b32 v60, v189, v47
	v_rcp_f32_e32 v57, v57
	v_exp_f32_e32 v64, v64
	s_waitcnt lgkmcnt(0)
	v_add_f32_e32 v47, v47, v60
	v_mul_f32_e32 v60, 0x3b000000, v47
	v_pk_add_f32 v[54:55], v[54:55], v[60:61] op_sel_hi:[1,0] neg_lo:[0,1] neg_hi:[0,1]
	v_pk_mul_f32 v[52:53], v[52:53], v[56:57]
	v_add_f32_e32 v57, 1.0, v64
	v_pk_mul_f32 v[64:65], v[54:55], v[54:55]
	v_pk_add_f32 v[50:51], v[50:51], v[60:61] op_sel_hi:[1,0] neg_lo:[0,1] neg_hi:[0,1]
	v_add_f32_e32 v47, v64, v65
	v_pk_mul_f32 v[66:67], v[50:51], v[50:51]
	v_pk_add_f32 v[68:69], v[44:45], v[60:61] op_sel_hi:[1,0] neg_lo:[0,1] neg_hi:[0,1]
	v_add_f32_e32 v47, v47, v66
	v_pk_mul_f32 v[44:45], v[68:69], v[68:69]
	v_add_f32_e32 v47, v47, v67
	v_add_f32_e32 v56, 1.0, v61
	v_pk_add_f32 v[60:61], v[42:43], v[60:61] op_sel_hi:[1,0] neg_lo:[0,1] neg_hi:[0,1]
	v_add_f32_e32 v44, v47, v44
	v_pk_mul_f32 v[42:43], v[60:61], v[60:61]
	v_add_f32_e32 v44, v44, v45
	v_add_f32_e32 v42, v44, v42
	v_add_f32_e32 v44, v42, v43
	ds_bpermute_b32 v45, v184, v44
	v_pk_mul_f32 v[42:43], v[46:47], v[62:63] op_sel_hi:[0,1]
	v_pk_fma_f32 v[42:43], v[42:43], v[28:29], v[32:33]
	v_rcp_f32_e32 v56, v56
	v_mul_f32_e32 v46, 0xbfb8aa3b, v42
	s_waitcnt lgkmcnt(0)
	v_add_f32_e32 v44, v44, v45
	ds_bpermute_b32 v45, v185, v44
	v_exp_f32_e32 v46, v46
	v_mul_f32_e32 v47, 0xbfb8aa3b, v43
	v_rcp_f32_e32 v57, v57
	v_exp_f32_e32 v47, v47
	s_waitcnt lgkmcnt(0)
; __device__ __forceinline__ unsigned pkh8(float lo, float hi) { return rnd8a(pkh(lo, hi)); }
; __device__ __forceinline__ float sigmoidf_(float x) { return __builtin_amdgcn_rcpf(1.0f + __builtin_amdgcn_exp2f(-x * LOG2E)); }
; __global__ void __launch_bounds__(NWAVES * 64, 2) fwd_kernel(Args args) {
;     ...
;                 for (int i = 0; i < 8; ++i) { const float mu = sm[i] * (1.0f / CONV_CH); sm[i] = mu; float q_ = 0.f;
; #pragma unroll
;                     for (int e = 0; e < 8; ++e) { acc[i][e] -= mu; q_ += acc[i][e] * acc[i][e]; }
;                     sq[i] = q_; }
;                 wave_sum_n<8>(sq);
; #pragma unroll
;                 for (int i = 0; i < 8; ++i) {
;                     const float rstd = __builtin_amdgcn_rsqf(sq[i] * (1.0f / CONV_CH) + EPS);
;                     float y[8];
; #pragma unroll
;                     for (int e = 0; e < 8; ++e) { const float z = acc[i][e] * rstd * gam[e] + bet[e]; y[e] = z * sigmoidf_(z); }
;                     u32x4 w; w.x = pkh8(y[0], y[1]); w.y = pkh8(y[2], y[3]); w.z = pkh8(y[4], y[5]); w.w = pkh8(y[6], y[7]);
;                     *(u32x4*)(MIX + (size_t)(t0 + wave * 8 + i) * D + c0) = w;
;                 }
	v_add_f32_e32 v62, v44, v45
	ds_bpermute_b32 v63, v186, v62
	v_add_f32_e32 v46, 1.0, v46
	v_rcp_f32_e32 v44, v46
	v_add_f32_e32 v45, 1.0, v47
	v_pk_mul_f32 v[46:47], v[58:59], v[56:57]
	s_waitcnt lgkmcnt(0)
	v_add_f32_e32 v58, v62, v63
	ds_bpermute_b32 v59, v187, v58
	v_rcp_f32_e32 v45, v45
	v_cvt_pk_f16_f32 v46, v46, v47
	v_pk_mul_f32 v[56:57], v[42:43], v[44:45]
	s_waitcnt lgkmcnt(0)
	v_add_f32_e32 v44, v58, v59
	ds_bpermute_b32 v45, v188, v44
	v_cvt_pk_f16_f32 v42, v48, v49
	v_cvt_pk_f16_f32 v43, v52, v53
	v_add_u32_e32 v42, 0x40004, v42
	v_add_u32_e32 v43, 0x40004, v43
	s_waitcnt lgkmcnt(0)
	v_add_f32_e32 v45, v44, v45
	ds_bpermute_b32 v47, v189, v45
	v_add_u32_e32 v44, 0x40004, v46
	v_cvt_pk_f16_f32 v46, v56, v57
	v_add_u32_e32 v48, 0x40004, v46
	v_and_b32_e32 v42, 0xfff8fff8, v42
	s_waitcnt lgkmcnt(0)
	v_add_f32_e32 v45, v45, v47
	v_fmamk_f32 v45, v45, 0x3b000000, v207
	v_rsq_f32_e32 v46, v45
	v_and_b32_e32 v45, 0xfff8fff8, v48
	v_and_b32_e32 v43, 0xfff8fff8, v43
	v_and_b32_e32 v44, 0xfff8fff8, v44
	v_pk_mul_f32 v[48:49], v[46:47], v[54:55] op_sel_hi:[0,1]
	v_pk_add_f32 v[54:55], v[18:19], v[140:141]
	v_lshl_add_u64 v[52:53], v[104:105], 0, s[8:9]
	v_add_f32_e32 v56, 0, v54
	global_store_dwordx4 v[52:53], v[42:45], off
	v_pk_add_f32 v[52:53], v[20:21], v[138:139]
	v_add_f32_e32 v56, v56, v55
	v_add_f32_e32 v56, v56, v52
	v_pk_fma_f32 v[48:49], v[48:49], v[34:35], v[38:39]
	v_pk_add_f32 v[44:45], v[22:23], v[136:137]
	v_add_f32_e32 v56, v56, v53
	v_mul_f32_e32 v42, 0xbfb8aa3b, v49
	v_add_f32_e32 v56, v56, v44
	v_exp_f32_e32 v57, v42
	v_pk_add_f32 v[42:43], v[24:25], v[134:135]
	v_add_f32_e32 v56, v56, v45
	v_mul_f32_e32 v47, 0xbfb8aa3b, v48
	v_add_f32_e32 v56, v56, v42
	v_exp_f32_e32 v47, v47
	v_add_f32_e32 v58, v56, v43
	ds_bpermute_b32 v59, v184, v58
	s_or_b32 s8, s0, 4
	v_add_f32_e32 v47, 1.0, v47
	v_rcp_f32_e32 v56, v47
	v_add_f32_e32 v47, 1.0, v57
	v_rcp_f32_e32 v57, v47
	v_pk_mul_f32 v[50:51], v[46:47], v[50:51] op_sel_hi:[0,1]
	s_waitcnt lgkmcnt(0)
	v_add_f32_e32 v47, v58, v59
	ds_bpermute_b32 v58, v185, v47
	v_pk_mul_f32 v[48:49], v[48:49], v[56:57]
	v_pk_fma_f32 v[50:51], v[50:51], v[36:37], v[40:41]
	s_ashr_i32 s9, s8, 31
	v_mul_f32_e32 v59, 0xbfb8aa3b, v50
	s_waitcnt lgkmcnt(0)
	v_add_f32_e32 v47, v47, v58
	ds_bpermute_b32 v57, v186, v47
	v_mul_f32_e32 v58, 0xbfb8aa3b, v51
	v_exp_f32_e32 v59, v59
	v_exp_f32_e32 v58, v58
	s_lshl_b64 s[8:9], s[8:9], 11
	s_waitcnt lgkmcnt(0)
	v_add_f32_e32 v47, v47, v57
	ds_bpermute_b32 v62, v187, v47
	v_add_f32_e32 v56, 1.0, v59
	v_add_f32_e32 v57, 1.0, v58
	v_pk_mul_f32 v[58:59], v[46:47], v[68:69] op_sel_hi:[0,1]
	v_pk_fma_f32 v[58:59], v[58:59], v[26:27], v[30:31]
	s_waitcnt lgkmcnt(0)
	v_add_f32_e32 v47, v47, v62
	ds_bpermute_b32 v62, v188, v47
	v_mul_f32_e32 v63, 0xbfb8aa3b, v58
	v_exp_f32_e32 v63, v63
	v_mul_f32_e32 v64, 0xbfb8aa3b, v59
	v_rcp_f32_e32 v56, v56
	s_waitcnt lgkmcnt(0)
	v_add_f32_e32 v47, v47, v62
	ds_bpermute_b32 v62, v189, v47
	v_rcp_f32_e32 v57, v57
	v_exp_f32_e32 v64, v64
	s_waitcnt lgkmcnt(0)
	v_add_f32_e32 v47, v47, v62
	v_mul_f32_e32 v62, 0x3b000000, v47
	v_pk_add_f32 v[54:55], v[54:55], v[62:63] op_sel_hi:[1,0] neg_lo:[0,1] neg_hi:[0,1]
	v_pk_mul_f32 v[50:51], v[50:51], v[56:57]
	v_add_f32_e32 v57, 1.0, v64
	v_pk_mul_f32 v[64:65], v[54:55], v[54:55]
	v_pk_add_f32 v[52:53], v[52:53], v[62:63] op_sel_hi:[1,0] neg_lo:[0,1] neg_hi:[0,1]
	v_add_f32_e32 v47, v64, v65
	v_pk_mul_f32 v[66:67], v[52:53], v[52:53]
	v_pk_add_f32 v[68:69], v[44:45], v[62:63] op_sel_hi:[1,0] neg_lo:[0,1] neg_hi:[0,1]
	v_add_f32_e32 v47, v47, v66
	v_pk_mul_f32 v[44:45], v[68:69], v[68:69]
	v_add_f32_e32 v47, v47, v67
	v_add_f32_e32 v56, 1.0, v63
	v_pk_add_f32 v[62:63], v[42:43], v[62:63] op_sel_hi:[1,0] neg_lo:[0,1] neg_hi:[0,1]
	v_add_f32_e32 v44, v47, v44
	v_pk_mul_f32 v[42:43], v[62:63], v[62:63]
	v_add_f32_e32 v44, v44, v45
	v_add_f32_e32 v42, v44, v42
	v_add_f32_e32 v44, v42, v43
	ds_bpermute_b32 v45, v184, v44
	v_pk_mul_f32 v[42:43], v[46:47], v[60:61] op_sel_hi:[0,1]
	v_pk_fma_f32 v[42:43], v[42:43], v[28:29], v[32:33]
	v_rcp_f32_e32 v56, v56
	v_mul_f32_e32 v46, 0xbfb8aa3b, v42
	s_waitcnt lgkmcnt(0)
	v_add_f32_e32 v44, v44, v45
	ds_bpermute_b32 v45, v185, v44
	v_exp_f32_e32 v46, v46
	v_mul_f32_e32 v47, 0xbfb8aa3b, v43
	v_rcp_f32_e32 v57, v57
	v_exp_f32_e32 v47, v47
	s_waitcnt lgkmcnt(0)
	v_add_f32_e32 v60, v44, v45
	ds_bpermute_b32 v61, v186, v60
	v_add_f32_e32 v46, 1.0, v46
	v_rcp_f32_e32 v44, v46
	v_add_f32_e32 v45, 1.0, v47
	v_pk_mul_f32 v[46:47], v[58:59], v[56:57]
	s_waitcnt lgkmcnt(0)
	v_add_f32_e32 v58, v60, v61
	ds_bpermute_b32 v59, v187, v58
	v_rcp_f32_e32 v45, v45
	v_cvt_pk_f16_f32 v46, v46, v47
	v_pk_mul_f32 v[56:57], v[42:43], v[44:45]
	s_waitcnt lgkmcnt(0)
	v_add_f32_e32 v44, v58, v59
	ds_bpermute_b32 v45, v188, v44
	v_cvt_pk_f16_f32 v42, v48, v49
	v_cvt_pk_f16_f32 v43, v50, v51
	v_add_u32_e32 v42, 0x40004, v42
	v_add_u32_e32 v43, 0x40004, v43
	s_waitcnt lgkmcnt(0)
	v_add_f32_e32 v45, v44, v45
	ds_bpermute_b32 v47, v189, v45
	v_add_u32_e32 v44, 0x40004, v46
	v_cvt_pk_f16_f32 v46, v56, v57
	v_add_u32_e32 v48, 0x40004, v46
	v_and_b32_e32 v42, 0xfff8fff8, v42
	s_waitcnt lgkmcnt(0)
; __device__ __forceinline__ unsigned pkh8(float lo, float hi) { return rnd8a(pkh(lo, hi)); }
; __device__ __forceinline__ float sigmoidf_(float x) { return __builtin_amdgcn_rcpf(1.0f + __builtin_amdgcn_exp2f(-x * LOG2E)); }
; __global__ void __launch_bounds__(NWAVES * 64, 2) fwd_kernel(Args args) {
;     ...
;                 for (int i = 0; i < 8; ++i) { const float mu = sm[i] * (1.0f / CONV_CH); sm[i] = mu; float q_ = 0.f;
; #pragma unroll
;                     for (int e = 0; e < 8; ++e) { acc[i][e] -= mu; q_ += acc[i][e] * acc[i][e]; }
;                     sq[i] = q_; }
;                 wave_sum_n<8>(sq);
; #pragma unroll
;                 for (int i = 0; i < 8; ++i) {
;                     const float rstd = __builtin_amdgcn_rsqf(sq[i] * (1.0f / CONV_CH) + EPS);
;                     float y[8];
; #pragma unroll
;                     for (int e = 0; e < 8; ++e) { const float z = acc[i][e] * rstd * gam[e] + bet[e]; y[e] = z * sigmoidf_(z); }
;                     u32x4 w; w.x = pkh8(y[0], y[1]); w.y = pkh8(y[2], y[3]); w.z = pkh8(y[4], y[5]); w.w = pkh8(y[6], y[7]);
;                     *(u32x4*)(MIX + (size_t)(t0 + wave * 8 + i) * D + c0) = w;
;                 }
	v_add_f32_e32 v45, v45, v47
	v_fmamk_f32 v45, v45, 0x3b000000, v207
	v_rsq_f32_e32 v46, v45
	v_and_b32_e32 v45, 0xfff8fff8, v48
	v_and_b32_e32 v43, 0xfff8fff8, v43
	v_and_b32_e32 v44, 0xfff8fff8, v44
	v_pk_mul_f32 v[48:49], v[46:47], v[54:55] op_sel_hi:[0,1]
	v_pk_fma_f32 v[48:49], v[48:49], v[34:35], v[38:39]
	v_lshl_add_u64 v[50:51], v[104:105], 0, s[8:9]
	v_mul_f32_e32 v47, 0xbfb8aa3b, v48
	v_exp_f32_e32 v47, v47
	v_pk_add_f32 v[56:57], v[18:19], v[132:133]
	global_store_dwordx4 v[50:51], v[42:45], off
	v_pk_add_f32 v[54:55], v[20:21], v[130:131]
	v_pk_add_f32 v[50:51], v[22:23], v[128:129]
	v_add_f32_e32 v42, 1.0, v47
	v_add_f32_e32 v47, 0, v56
	v_add_f32_e32 v47, v47, v57
	v_add_f32_e32 v47, v47, v54
	v_add_f32_e32 v47, v47, v55
	v_add_f32_e32 v47, v47, v50
	v_pk_add_f32 v[44:45], v[24:25], v[126:127]
	v_add_f32_e32 v47, v47, v51
	v_add_f32_e32 v47, v47, v44
	v_add_f32_e32 v47, v47, v45
	ds_bpermute_b32 v58, v184, v47
	v_pk_mul_f32 v[52:53], v[46:47], v[52:53] op_sel_hi:[0,1]
	v_pk_fma_f32 v[52:53], v[52:53], v[36:37], v[40:41]
	v_mul_f32_e32 v43, 0xbfb8aa3b, v49
	v_mul_f32_e32 v59, 0xbfb8aa3b, v52
	s_waitcnt lgkmcnt(0)
	v_add_f32_e32 v47, v47, v58
	ds_bpermute_b32 v58, v185, v47
	v_mul_f32_e32 v60, 0xbfb8aa3b, v53
	v_exp_f32_e32 v59, v59
	v_exp_f32_e32 v60, v60
	v_exp_f32_e32 v43, v43
	s_waitcnt lgkmcnt(0)
	v_add_f32_e32 v47, v47, v58
	ds_bpermute_b32 v64, v186, v47
	v_add_f32_e32 v58, 1.0, v59
	v_add_f32_e32 v59, 1.0, v60
	v_pk_mul_f32 v[60:61], v[46:47], v[68:69] op_sel_hi:[0,1]
	v_pk_fma_f32 v[60:61], v[60:61], v[26:27], v[30:31]
	s_waitcnt lgkmcnt(0)
	v_add_f32_e32 v47, v47, v64
	ds_bpermute_b32 v64, v187, v47
	v_mul_f32_e32 v65, 0xbfb8aa3b, v60
	v_exp_f32_e32 v65, v65
	v_add_f32_e32 v43, 1.0, v43
	v_rcp_f32_e32 v42, v42
	s_waitcnt lgkmcnt(0)
	v_add_f32_e32 v47, v47, v64
	ds_bpermute_b32 v66, v188, v47
	v_add_f32_e32 v64, 1.0, v65
	v_mul_f32_e32 v65, 0xbfb8aa3b, v61
	v_exp_f32_e32 v65, v65
	v_rcp_f32_e32 v43, v43
	s_waitcnt lgkmcnt(0)
	v_add_f32_e32 v66, v47, v66
	ds_bpermute_b32 v67, v189, v66
	v_add_f32_e32 v47, 1.0, v65
	v_rcp_f32_e32 v65, v47
	v_pk_mul_f32 v[46:47], v[46:47], v[62:63] op_sel_hi:[0,1]
	v_pk_fma_f32 v[46:47], v[46:47], v[28:29], v[32:33]
	s_waitcnt lgkmcnt(0)
	v_add_f32_e32 v62, v66, v67
	v_mul_f32_e32 v62, 0x3b000000, v62
	v_pk_add_f32 v[56:57], v[56:57], v[62:63] op_sel_hi:[1,0] neg_lo:[0,1] neg_hi:[0,1]
	v_pk_add_f32 v[54:55], v[54:55], v[62:63] op_sel_hi:[1,0] neg_lo:[0,1] neg_hi:[0,1]
	v_pk_mul_f32 v[66:67], v[56:57], v[56:57]
	v_pk_mul_f32 v[68:69], v[54:55], v[54:55]
	v_add_f32_e32 v66, v66, v67
	v_pk_add_f32 v[50:51], v[50:51], v[62:63] op_sel_hi:[1,0] neg_lo:[0,1] neg_hi:[0,1]
	v_add_f32_e32 v66, v66, v68
	v_pk_mul_f32 v[70:71], v[50:51], v[50:51]
	v_add_f32_e32 v66, v66, v69
	v_pk_add_f32 v[62:63], v[44:45], v[62:63] op_sel_hi:[1,0] neg_lo:[0,1] neg_hi:[0,1]
	v_add_f32_e32 v66, v66, v70
	v_pk_mul_f32 v[44:45], v[62:63], v[62:63]
	v_add_f32_e32 v66, v66, v71
	v_add_f32_e32 v44, v66, v44
	v_add_f32_e32 v44, v44, v45
	ds_bpermute_b32 v45, v184, v44
	v_mul_f32_e32 v66, 0xbfb8aa3b, v46
	v_exp_f32_e32 v66, v66
	v_mul_f32_e32 v67, 0xbfb8aa3b, v47
	v_exp_f32_e32 v67, v67
	s_waitcnt lgkmcnt(0)
	v_add_f32_e32 v68, v44, v45
	ds_bpermute_b32 v69, v185, v68
	v_add_f32_e32 v44, 1.0, v66
	v_add_f32_e32 v45, 1.0, v67
	v_rcp_f32_e32 v44, v44
	v_rcp_f32_e32 v45, v45
	s_waitcnt lgkmcnt(0)
	v_add_f32_e32 v66, v68, v69
	ds_bpermute_b32 v67, v186, v66
	v_rcp_f32_e32 v58, v58
	v_pk_mul_f32 v[46:47], v[46:47], v[44:45]
	v_rcp_f32_e32 v59, v59
	v_rcp_f32_e32 v64, v64
	s_waitcnt lgkmcnt(0)
	v_add_f32_e32 v44, v66, v67
	ds_bpermute_b32 v45, v187, v44
	v_pk_mul_f32 v[42:43], v[48:49], v[42:43]
	v_pk_mul_f32 v[48:49], v[52:53], v[58:59]
	v_pk_mul_f32 v[52:53], v[60:61], v[64:65]
	v_cvt_pk_f16_f32 v42, v42, v43
	s_waitcnt lgkmcnt(0)
	v_add_f32_e32 v44, v44, v45
	ds_bpermute_b32 v45, v188, v44
	v_cvt_pk_f16_f32 v43, v48, v49
	v_cvt_pk_f16_f32 v48, v52, v53
	v_add_u32_e32 v48, 0x40004, v48
	v_pk_add_f32 v[18:19], v[18:19], v[124:125]
	s_waitcnt lgkmcnt(0)
	v_add_f32_e32 v49, v44, v45
	ds_bpermute_b32 v52, v189, v49
	v_cvt_pk_f16_f32 v45, v46, v47
	v_and_b32_e32 v44, 0xfff8fff8, v48
	v_pk_add_f32 v[20:21], v[20:21], v[122:123]
	v_pk_add_f32 v[22:23], v[22:23], v[120:121]
	s_waitcnt lgkmcnt(0)
	v_add_f32_e32 v46, v49, v52
	v_fmamk_f32 v46, v46, 0x3b000000, v207
	v_rsq_f32_e32 v46, v46
	v_pk_add_f32 v[24:25], v[24:25], v[118:119]
	s_or_b32 s8, s0, 5
	s_ashr_i32 s9, s8, 31
	v_pk_mul_f32 v[48:49], v[46:47], v[56:57] op_sel_hi:[0,1]
	v_pk_fma_f32 v[48:49], v[48:49], v[34:35], v[38:39]
	v_add_u32_e32 v42, 0x40004, v42
	v_mul_f32_e32 v47, 0xbfb8aa3b, v48
	v_exp_f32_e32 v47, v47
	v_mul_f32_e32 v52, 0xbfb8aa3b, v49
	v_exp_f32_e32 v57, v52
	v_add_u32_e32 v43, 0x40004, v43
	v_add_f32_e32 v47, 1.0, v47
	v_rcp_f32_e32 v56, v47
	v_add_f32_e32 v47, 1.0, v57
	v_rcp_f32_e32 v57, v47
	v_add_f32_e32 v47, 0, v18
	v_add_f32_e32 v47, v47, v19
	v_add_f32_e32 v47, v47, v20
	v_add_f32_e32 v47, v47, v21
	v_add_f32_e32 v47, v47, v22
	v_add_f32_e32 v47, v47, v23
	v_add_f32_e32 v47, v47, v24
	v_add_f32_e32 v47, v47, v25
	ds_bpermute_b32 v58, v184, v47
	v_add_u32_e32 v45, 0x40004, v45
	s_lshl_b64 s[8:9], s[8:9], 11
	v_and_b32_e32 v42, 0xfff8fff8, v42
	v_and_b32_e32 v43, 0xfff8fff8, v43
	v_and_b32_e32 v45, 0xfff8fff8, v45
	v_lshl_add_u64 v[52:53], v[104:105], 0, s[8:9]
	global_store_dwordx4 v[52:53], v[42:45], off
	s_or_b32 s8, s0, 6
	s_ashr_i32 s9, s8, 31
	v_pk_mul_f32 v[44:45], v[46:47], v[54:55] op_sel_hi:[0,1]
	s_waitcnt lgkmcnt(0)
; __device__ __forceinline__ unsigned pkh8(float lo, float hi) { return rnd8a(pkh(lo, hi)); }
; __device__ __forceinline__ float sigmoidf_(float x) { return __builtin_amdgcn_rcpf(1.0f + __builtin_amdgcn_exp2f(-x * LOG2E)); }
; __global__ void __launch_bounds__(NWAVES * 64, 2) fwd_kernel(Args args) {
;     ...
;                 for (int i = 0; i < 8; ++i) { const float mu = sm[i] * (1.0f / CONV_CH); sm[i] = mu; float q_ = 0.f;
; #pragma unroll
;                     for (int e = 0; e < 8; ++e) { acc[i][e] -= mu; q_ += acc[i][e] * acc[i][e]; }
;                     sq[i] = q_; }
;                 wave_sum_n<8>(sq);
; #pragma unroll
;                 for (int i = 0; i < 8; ++i) {
;                     const float rstd = __builtin_amdgcn_rsqf(sq[i] * (1.0f / CONV_CH) + EPS);
;                     float y[8];
; #pragma unroll
;                     for (int e = 0; e < 8; ++e) { const float z = acc[i][e] * rstd * gam[e] + bet[e]; y[e] = z * sigmoidf_(z); }
;                     u32x4 w; w.x = pkh8(y[0], y[1]); w.y = pkh8(y[2], y[3]); w.z = pkh8(y[4], y[5]); w.w = pkh8(y[6], y[7]);
;                     *(u32x4*)(MIX + (size_t)(t0 + wave * 8 + i) * D + c0) = w;
;                 }
;             }
	v_add_f32_e32 v47, v47, v58
	v_pk_mul_f32 v[42:43], v[48:49], v[56:57]
	ds_bpermute_b32 v48, v185, v47
	v_pk_fma_f32 v[44:45], v[44:45], v[36:37], v[40:41]
	s_lshl_b64 s[8:9], s[8:9], 11
	v_mul_f32_e32 v49, 0xbfb8aa3b, v44
	v_mul_f32_e32 v52, 0xbfb8aa3b, v45
	s_waitcnt lgkmcnt(0)
	v_add_f32_e32 v47, v47, v48
	ds_bpermute_b32 v53, v186, v47
	v_exp_f32_e32 v49, v49
	v_exp_f32_e32 v52, v52
	v_pk_mul_f32 v[50:51], v[46:47], v[50:51] op_sel_hi:[0,1]
	v_pk_fma_f32 v[50:51], v[50:51], v[26:27], v[30:31]
	s_waitcnt lgkmcnt(0)
	v_add_f32_e32 v47, v47, v53
	v_add_f32_e32 v48, 1.0, v49
	v_add_f32_e32 v49, 1.0, v52
	ds_bpermute_b32 v52, v187, v47
	v_mul_f32_e32 v53, 0xbfb8aa3b, v50
	v_exp_f32_e32 v53, v53
	v_rcp_f32_e32 v48, v48
	v_rcp_f32_e32 v49, v49
	s_waitcnt lgkmcnt(0)
	v_add_f32_e32 v47, v47, v52
	ds_bpermute_b32 v54, v188, v47
	v_add_f32_e32 v52, 1.0, v53
	v_mul_f32_e32 v53, 0xbfb8aa3b, v51
	v_exp_f32_e32 v53, v53
	v_rcp_f32_e32 v52, v52
	s_waitcnt lgkmcnt(0)
	v_add_f32_e32 v54, v47, v54
	ds_bpermute_b32 v55, v189, v54
	v_add_f32_e32 v47, 1.0, v53
	v_rcp_f32_e32 v53, v47
	v_pk_mul_f32 v[46:47], v[46:47], v[62:63] op_sel_hi:[0,1]
	v_pk_fma_f32 v[46:47], v[46:47], v[28:29], v[32:33]
	s_waitcnt lgkmcnt(0)
	v_add_f32_e32 v54, v54, v55
	v_mul_f32_e32 v54, 0x3b000000, v54
	v_pk_add_f32 v[56:57], v[18:19], v[54:55] op_sel_hi:[1,0] neg_lo:[0,1] neg_hi:[0,1]
	v_pk_add_f32 v[58:59], v[20:21], v[54:55] op_sel_hi:[1,0] neg_lo:[0,1] neg_hi:[0,1]
	v_pk_mul_f32 v[18:19], v[56:57], v[56:57]
	v_pk_mul_f32 v[20:21], v[58:59], v[58:59]
	v_add_f32_e32 v18, v18, v19
	v_pk_add_f32 v[22:23], v[22:23], v[54:55] op_sel_hi:[1,0] neg_lo:[0,1] neg_hi:[0,1]
	v_add_f32_e32 v18, v18, v20
	v_pk_mul_f32 v[60:61], v[22:23], v[22:23]
	v_add_f32_e32 v18, v18, v21
	v_pk_add_f32 v[24:25], v[24:25], v[54:55] op_sel_hi:[1,0] neg_lo:[0,1] neg_hi:[0,1]
	v_add_f32_e32 v18, v18, v60
	v_pk_mul_f32 v[54:55], v[24:25], v[24:25]
	v_add_f32_e32 v18, v18, v61
	v_add_f32_e32 v18, v18, v54
	v_add_f32_e32 v18, v18, v55
	ds_bpermute_b32 v19, v184, v18
	v_mul_f32_e32 v20, 0xbfb8aa3b, v46
	v_mul_f32_e32 v21, 0xbfb8aa3b, v47
	v_exp_f32_e32 v20, v20
	v_exp_f32_e32 v21, v21
	s_waitcnt lgkmcnt(0)
	v_add_f32_e32 v54, v18, v19
	ds_bpermute_b32 v55, v185, v54
	v_add_f32_e32 v18, 1.0, v20
	v_add_f32_e32 v19, 1.0, v21
	v_rcp_f32_e32 v18, v18
	v_rcp_f32_e32 v19, v19
	s_waitcnt lgkmcnt(0)
	v_add_f32_e32 v54, v54, v55
	ds_bpermute_b32 v55, v186, v54
	v_pk_mul_f32 v[20:21], v[44:45], v[48:49]
	v_pk_mul_f32 v[46:47], v[46:47], v[18:19]
	v_cvt_pk_f16_f32 v18, v42, v43
	v_cvt_pk_f16_f32 v20, v20, v21
	s_waitcnt lgkmcnt(0)
	v_add_f32_e32 v19, v54, v55
	ds_bpermute_b32 v42, v187, v19
	v_pk_mul_f32 v[44:45], v[50:51], v[52:53]
	v_add_u32_e32 v20, 0x40004, v20
	v_add_u32_e32 v18, 0x40004, v18
	v_and_b32_e32 v18, 0xfff8fff8, v18
	s_waitcnt lgkmcnt(0)
	v_add_f32_e32 v21, v19, v42
	ds_bpermute_b32 v42, v188, v21
	v_and_b32_e32 v19, 0xfff8fff8, v20
	v_cvt_pk_f16_f32 v20, v44, v45
	v_add_u32_e32 v20, 0x40004, v20
	v_and_b32_e32 v20, 0xfff8fff8, v20
	s_waitcnt lgkmcnt(0)
	v_add_f32_e32 v42, v21, v42
	ds_bpermute_b32 v43, v189, v42
	v_cvt_pk_f16_f32 v21, v46, v47
	v_add_u32_e32 v21, 0x40004, v21
	v_and_b32_e32 v21, 0xfff8fff8, v21
	v_lshl_add_u64 v[44:45], v[104:105], 0, s[8:9]
	s_waitcnt lgkmcnt(0)
	v_add_f32_e32 v42, v42, v43
	v_fmamk_f32 v42, v42, 0x3b000000, v207
	v_rsq_f32_e32 v42, v42
	global_store_dwordx4 v[44:45], v[18:21], off
	s_or_b32 s0, s0, 7
	s_ashr_i32 s1, s0, 31
	v_pk_mul_f32 v[46:47], v[42:43], v[56:57] op_sel_hi:[0,1]
	v_pk_mul_f32 v[20:21], v[42:43], v[58:59] op_sel_hi:[0,1]
	v_pk_mul_f32 v[22:23], v[42:43], v[22:23] op_sel_hi:[0,1]
	v_pk_mul_f32 v[24:25], v[42:43], v[24:25] op_sel_hi:[0,1]
	v_pk_fma_f32 v[34:35], v[46:47], v[34:35], v[38:39]
	v_pk_fma_f32 v[20:21], v[20:21], v[36:37], v[40:41]
	v_pk_fma_f32 v[22:23], v[22:23], v[26:27], v[30:31]
	v_pk_fma_f32 v[24:25], v[24:25], v[28:29], v[32:33]
	v_mul_f32_e32 v38, 0xbfb8aa3b, v34
	v_mul_f32_e32 v39, 0xbfb8aa3b, v35
	v_mul_f32_e32 v36, 0xbfb8aa3b, v20
	v_mul_f32_e32 v37, 0xbfb8aa3b, v21
	v_mul_f32_e32 v26, 0xbfb8aa3b, v22
	v_mul_f32_e32 v27, 0xbfb8aa3b, v23
	v_mul_f32_e32 v28, 0xbfb8aa3b, v24
	v_mul_f32_e32 v29, 0xbfb8aa3b, v25
	v_exp_f32_e32 v38, v38
	v_exp_f32_e32 v39, v39
	v_exp_f32_e32 v36, v36
	v_exp_f32_e32 v37, v37
	v_exp_f32_e32 v26, v26
	v_exp_f32_e32 v27, v27
	v_exp_f32_e32 v28, v28
	v_exp_f32_e32 v29, v29
	v_add_f32_e32 v18, 1.0, v38
	v_add_f32_e32 v19, 1.0, v39
	v_add_f32_e32 v36, 1.0, v36
	v_add_f32_e32 v37, 1.0, v37
	v_add_f32_e32 v26, 1.0, v26
	v_add_f32_e32 v27, 1.0, v27
	v_add_f32_e32 v28, 1.0, v28
	v_add_f32_e32 v29, 1.0, v29
	v_rcp_f32_e32 v18, v18
	v_rcp_f32_e32 v19, v19
	v_rcp_f32_e32 v36, v36
	v_rcp_f32_e32 v37, v37
	v_rcp_f32_e32 v26, v26
	v_rcp_f32_e32 v27, v27
	v_rcp_f32_e32 v28, v28
	v_rcp_f32_e32 v29, v29
	v_pk_mul_f32 v[18:19], v[34:35], v[18:19]
	v_pk_mul_f32 v[20:21], v[20:21], v[36:37]
	v_pk_mul_f32 v[22:23], v[22:23], v[26:27]
	v_pk_mul_f32 v[24:25], v[24:25], v[28:29]
	v_cvt_pk_f16_f32 v18, v18, v19
	v_cvt_pk_f16_f32 v19, v20, v21
	v_cvt_pk_f16_f32 v20, v22, v23
	v_cvt_pk_f16_f32 v21, v24, v25
	v_add_u32_e32 v18, 0x40004, v18
	v_add_u32_e32 v19, 0x40004, v19
	v_add_u32_e32 v20, 0x40004, v20
	v_add_u32_e32 v21, 0x40004, v21
	s_lshl_b64 s[0:1], s[0:1], 11
	v_and_b32_e32 v18, 0xfff8fff8, v18
	v_and_b32_e32 v19, 0xfff8fff8, v19
	v_and_b32_e32 v20, 0xfff8fff8, v20
	v_and_b32_e32 v21, 0xfff8fff8, v21
	v_lshl_add_u64 v[22:23], v[104:105], 0, s[0:1]
	s_cmpk_gt_i32 s11, 0xff
	s_mov_b64 s[0:1], 0
	global_store_dwordx4 v[22:23], v[18:21], off
	s_cbranch_scc0 .LBB0_627
